# v72 + P1/P12 stream split: converter workgroups run their (now bursty) idle-tail conversion after 1..11 units, staggered
# baseline (speedup 1.0000x reference)
.LBB0_1554:
	s_add_i32 s36, s3, 0x18000
	s_or_b32 s9, s61, 0x80
	s_mov_b32 s30, s90
	s_mov_b32 s31, s91
	s_mov_b32 m0, s36
	s_add_i32 s37, s3, 0x1a000
	s_waitcnt vmcnt(2)
	s_barrier
	buffer_load_dwordx4 v145, s[28:31], s9 offen lds
	s_mov_b32 m0, s37
	s_add_i32 s38, s3, 0x8000
	buffer_load_dwordx4 v149, s[28:31], s9 offen lds
	s_or_b32 s9, s60, 0x80
	s_mov_b32 m0, s38
	s_add_i32 s39, s3, 0xa000
	buffer_load_dwordx4 v143, s[88:91], s9 offen lds
	s_mov_b32 m0, s39
	s_add_i32 s40, s3, 0x1c000
	buffer_load_dwordx4 v147, s[88:91], s9 offen lds
	s_or_b32 s9, s61, 0x80080
	s_mov_b32 m0, s40
	s_add_i32 s41, s3, 0x1e000
	buffer_load_dwordx4 v145, s[28:31], s9 offen lds
	s_mov_b32 m0, s41
	s_lshl_b32 s43, s0, 6
	buffer_load_dwordx4 v149, s[28:31], s9 offen lds
	v_ashrrev_i32_e32 v1, 6, v0
	s_lshl_b32 s0, s0, 13
	v_and_b32_e32 v2, 48, v0
	v_lshl_add_u32 v3, v1, 10, s0
	v_lshlrev_b32_e32 v4, 6, v0
	s_movk_i32 s0, 0x3c0
	s_sext_i32_i16 s57, s1
	s_ashr_i32 s1, s8, 31
	v_and_or_b32 v2, v4, s0, v2
	v_readlane_b32 s0, v254, 16
	s_lshr_b32 s1, s1, 26
	s_lshl_b32 s0, s0, 5
	s_add_i32 s1, s8, s1
	s_and_b32 s44, s0, 0x60
	s_ashr_i32 s42, s1, 6
	s_lshr_b32 s0, s44, 3
	s_cmp_gt_i32 s8, 63
	v_add_lshl_u32 v1, v1, s0, 10
	s_cselect_b64 s[8:9], -1, 0
	s_add_i32 s45, s42, -2
	s_add_i32 s46, s3, 0xc000
	v_readlane_b32 s0, v254, 20
	v_lshlrev_b32_e32 v0, 2, v0
	s_cmpk_lt_u32 s0, 0x100
	v_and_b32_e32 v0, 32, v0
	s_waitcnt vmcnt(6)
	s_cselect_b64 s[10:11], -1, 0
	s_add_i32 s47, s3, 0xe000
	s_ashr_i32 s49, s33, 31
	v_bitop3_b32 v3, v2, v3, v0 bitop3:0xde
	v_bitop3_b32 v0, v2, v1, v0 bitop3:0xde
	s_add_u32 s12, s34, 0x6ac00
	s_mov_b32 s14, 0x3c010204
	s_addc_u32 s13, s35, 0
	v_mov_b64_e32 v[128:129], 0xb6c
	v_mov_b64_e32 v[130:131], 0xb6b
	v_readlane_b32 s0, v254, 16
	s_nop 3
	s_lshl_b32 s0, s0, 4
	s_add_i32 s0, s0, 0x23800
	s_nop 1
	v_mov_b32_e32 v130, s0
	ds_read_b32 v128, v130 offset:8
	s_waitcnt lgkmcnt(0)
	v_add_u32_e32 v130, -1, v128
	v_add_u32_e32 v150, 0, v0
	v_add_u32_e32 v151, 0, v3
	s_mov_b32 s15, 0x3d010204
	s_mov_b32 s50, 0xc3e00000
	s_movk_i32 s51, 0x2b00
	v_mov_b32_e32 v152, 0x43e00000
	s_barrier
	s_branch .LBB0_1557
